# hand-written local-attention wave item: pipelined K/V/bias loads, remapped items so a workgroup shares (b,h)
# speedup vs baseline: 1.0427x; 1.0427x over previous
.LBB0_479:
	s_andn2_b64 vcc, exec, s[0:1]
	s_cbranch_vccnz .LBB0_609
	s_sub_i32 s86, s12, s13
	s_and_b32 s0, s86, 3
	s_bfe_u32 s1, s86, 0x10002
	s_bfe_u32 s6, s86, 0x20003
	s_bfe_u32 s7, s86, 0x50005
	s_lshr_b32 s8, s86, 10
	s_lshl_b32 s7, s7, 1
	s_or_b32 s1, s1, s7
	s_sub_i32 s7, s1, 4
	s_max_i32 s7, s7, 0
	s_min_i32 s7, s7, 56
	s_lshl_b32 s9, s0, 4
	s_sub_i32 s9, s9, 8
	s_max_i32 s9, s9, 0
	s_min_i32 s9, s9, 32
	v_and_b32_e32 v206, 15, v205
	v_lshrrev_b32_e32 v207, 4, v205
	s_mul_i32 s10, s6, 15
	s_add_i32 s10, s10, s7
	s_sub_i32 s10, s10, s1
	s_add_i32 s10, s10, 7
	s_mul_i32 s10, s10, 31
	s_add_i32 s10, s10, s9
	s_lshl_b32 s11, s0, 4
	s_sub_i32 s10, s10, s11
	s_add_i32 s10, s10, 15
	v_lshlrev_b32_e32 v214, 3, v207
	v_sub_u32_e32 v214, v214, v206
	v_add_u32_e32 v214, s10, v214
	v_ashrrev_i32_e32 v215, 31, v214
	v_lshl_add_u64 v[212:213], v[214:215], 2, s[56:57]
	global_load_dword v0, v[212:213], off offset:0
	global_load_dword v1, v[212:213], off offset:4
	global_load_dword v2, v[212:213], off offset:8
	global_load_dword v3, v[212:213], off offset:12
	global_load_dword v4, v[212:213], off offset:16
	global_load_dword v5, v[212:213], off offset:20
	global_load_dword v6, v[212:213], off offset:24
	global_load_dword v7, v[212:213], off offset:28
	global_load_dword v8, v[212:213], off offset:124
	global_load_dword v9, v[212:213], off offset:128
	global_load_dword v10, v[212:213], off offset:132
	global_load_dword v11, v[212:213], off offset:136
	global_load_dword v12, v[212:213], off offset:140
	global_load_dword v13, v[212:213], off offset:144
	global_load_dword v14, v[212:213], off offset:148
	global_load_dword v15, v[212:213], off offset:152
	global_load_dword v16, v[212:213], off offset:248
	global_load_dword v17, v[212:213], off offset:252
	global_load_dword v18, v[212:213], off offset:256
	global_load_dword v19, v[212:213], off offset:260
	global_load_dword v20, v[212:213], off offset:264
	global_load_dword v21, v[212:213], off offset:268
	global_load_dword v22, v[212:213], off offset:272
	global_load_dword v23, v[212:213], off offset:276
	global_load_dword v24, v[212:213], off offset:372
	global_load_dword v25, v[212:213], off offset:376
	global_load_dword v26, v[212:213], off offset:380
	global_load_dword v27, v[212:213], off offset:384
	global_load_dword v28, v[212:213], off offset:388
	global_load_dword v29, v[212:213], off offset:392
	global_load_dword v30, v[212:213], off offset:396
	global_load_dword v31, v[212:213], off offset:400
	s_lshl_b32 s10, s8, 12
	s_lshl_b32 s11, s1, 6
	s_add_i32 s10, s10, s11
	s_lshl_b32 s11, s0, 4
	s_add_i32 s10, s10, s11
	s_addk_i32 s10, 0x400
	s_mul_i32 s11, s10, 0xe00
	s_lshl_b32 s16, s6, 7
	s_add_u32 s16, s16, 0x5e00000
	s_add_u32 s18, s4, s16
	s_addc_u32 s19, s5, 0
	s_add_u32 s20, s18, s11
	s_addc_u32 s21, s19, 0
	v_mul_u32_u24_e32 v208, 0xe00, v206
	v_lshl_add_u32 v208, v207, 4, v208
	global_load_dwordx4 v[128:131], v208, s[20:21] offset:1536
	global_load_dwordx4 v[132:135], v208, s[20:21] offset:1600
	v_lshrrev_b32_e32 v209, 2, v206
	v_and_b32_e32 v210, 3, v206
	v_lshl_add_u32 v209, v209, 3, v210
	v_mul_u32_u24_e32 v209, 0xe00, v209
	v_lshl_add_u32 v209, v207, 4, v209
	s_lshl_b32 s10, s8, 12
	s_lshl_b32 s11, s7, 6
	s_add_i32 s10, s10, s11
	s_add_i32 s10, s10, s9
	s_addk_i32 s10, 0x400
	s_mul_i32 s10, s10, 0xe00
	s_add_u32 s22, s18, s10
	s_addc_u32 s23, s19, 0
	s_lshl_b32 s10, s8, 8
	s_mul_i32 s10, s10, 0xe00
	s_add_u32 s24, s18, s10
	s_addc_u32 s25, s19, 0
	global_load_dwordx4 v[138:141], v209, s[22:23] offset:2048
	global_load_dwordx4 v[142:145], v209, s[22:23] offset:2112
	s_add_u32 s22, s22, 0x3800
	s_addc_u32 s23, s23, 0
	global_load_dwordx4 v[146:149], v209, s[22:23] offset:2048
	global_load_dwordx4 v[150:153], v209, s[22:23] offset:2112
	s_add_u32 s22, s22, 0x34800
	s_addc_u32 s23, s23, 0
	global_load_dwordx4 v[154:157], v209, s[22:23] offset:2048
	global_load_dwordx4 v[158:161], v209, s[22:23] offset:2112
	s_add_u32 s22, s22, 0x3800
	s_addc_u32 s23, s23, 0
	global_load_dwordx4 v[162:165], v209, s[22:23] offset:2048
	global_load_dwordx4 v[166:169], v209, s[22:23] offset:2112
	s_add_u32 s22, s22, 0x34800
	s_addc_u32 s23, s23, 0
	global_load_dwordx4 v[170:173], v209, s[22:23] offset:2048
	global_load_dwordx4 v[174:177], v209, s[22:23] offset:2112
	s_add_u32 s22, s22, 0x3800
	s_addc_u32 s23, s23, 0
	global_load_dwordx4 v[178:181], v209, s[22:23] offset:2048
	global_load_dwordx4 v[182:185], v209, s[22:23] offset:2112
	s_add_u32 s22, s22, 0x34800
	s_addc_u32 s23, s23, 0
	s_lshl_b32 s10, s0, 4
	s_sub_i32 s10, s10, 8
	v_add_u32_e32 v210, s10, v206
	v_med3_i32 v210, v210, 0, 48
	v_lshl_add_u32 v211, v207, 3, s9
	v_sub_u32_e32 v210, v211, v210
	v_writelane_b32 v136, s0, 0
	v_writelane_b32 v136, s1, 1
	v_writelane_b32 v136, s6, 2
	v_writelane_b32 v136, s7, 3
	v_writelane_b32 v136, s8, 4
	v_writelane_b32 v136, s9, 5
	v_add_u32_e32 v211, 0, v210
	v_cmp_gt_u32_e64 s[26:27], 16, v211
	v_add_u32_e32 v211, 1, v210
	v_cmp_gt_u32_e64 s[36:37], 16, v211
	v_add_u32_e32 v211, 2, v210
	v_cmp_gt_u32_e64 s[10:11], 16, v211
	v_add_u32_e32 v211, 3, v210
	v_cmp_gt_u32_e64 s[0:1], 16, v211
	v_add_u32_e32 v211, 4, v210
	v_cmp_gt_u32_e64 s[6:7], 16, v211
	v_add_u32_e32 v211, 5, v210
	v_cmp_gt_u32_e64 s[8:9], 16, v211
	v_add_u32_e32 v211, 6, v210
	v_cmp_gt_u32_e64 s[16:17], 16, v211
	v_add_u32_e32 v211, 7, v210
	v_cmp_gt_u32_e64 s[20:21], 16, v211
	v_mov_b32_e32 v216, 0xf2c9f2ca
	s_waitcnt vmcnt(14)
	v_mul_f32_e32 v0, 0x41000000, v0
	v_mul_f32_e32 v1, 0x41000000, v1
	v_mul_f32_e32 v2, 0x41000000, v2
	v_mul_f32_e32 v3, 0x41000000, v3
	v_mul_f32_e32 v4, 0x41000000, v4
	v_mul_f32_e32 v5, 0x41000000, v5
	v_mul_f32_e32 v6, 0x41000000, v6
	v_mul_f32_e32 v7, 0x41000000, v7
	v_cndmask_b32_e64 v0, v216, v0, s[26:27]
	v_cndmask_b32_e64 v1, v216, v1, s[36:37]
	v_cndmask_b32_e64 v2, v216, v2, s[10:11]
	v_cndmask_b32_e64 v3, v216, v3, s[0:1]
	v_cndmask_b32_e64 v4, v216, v4, s[6:7]
	v_cndmask_b32_e64 v5, v216, v5, s[8:9]
	v_cndmask_b32_e64 v6, v216, v6, s[16:17]
	v_cndmask_b32_e64 v7, v216, v7, s[20:21]
	v_mul_f32_e32 v8, 0x41000000, v8
	v_mul_f32_e32 v9, 0x41000000, v9
	v_mul_f32_e32 v10, 0x41000000, v10
	v_mul_f32_e32 v11, 0x41000000, v11
	v_mul_f32_e32 v12, 0x41000000, v12
	v_mul_f32_e32 v13, 0x41000000, v13
	v_mul_f32_e32 v14, 0x41000000, v14
	v_mul_f32_e32 v15, 0x41000000, v15
	v_cndmask_b32_e64 v8, v216, v8, s[26:27]
	v_cndmask_b32_e64 v9, v216, v9, s[36:37]
	v_cndmask_b32_e64 v10, v216, v10, s[10:11]
	v_cndmask_b32_e64 v11, v216, v11, s[0:1]
	v_cndmask_b32_e64 v12, v216, v12, s[6:7]
	v_cndmask_b32_e64 v13, v216, v13, s[8:9]
	v_cndmask_b32_e64 v14, v216, v14, s[16:17]
	v_cndmask_b32_e64 v15, v216, v15, s[20:21]
	v_mul_f32_e32 v16, 0x41000000, v16
	v_mul_f32_e32 v17, 0x41000000, v17
	v_mul_f32_e32 v18, 0x41000000, v18
	v_mul_f32_e32 v19, 0x41000000, v19
	v_mul_f32_e32 v20, 0x41000000, v20
	v_mul_f32_e32 v21, 0x41000000, v21
	v_mul_f32_e32 v22, 0x41000000, v22
	v_mul_f32_e32 v23, 0x41000000, v23
	v_cndmask_b32_e64 v16, v216, v16, s[26:27]
	v_cndmask_b32_e64 v17, v216, v17, s[36:37]
	v_cndmask_b32_e64 v18, v216, v18, s[10:11]
	v_cndmask_b32_e64 v19, v216, v19, s[0:1]
	v_cndmask_b32_e64 v20, v216, v20, s[6:7]
	v_cndmask_b32_e64 v21, v216, v21, s[8:9]
	v_cndmask_b32_e64 v22, v216, v22, s[16:17]
	v_cndmask_b32_e64 v23, v216, v23, s[20:21]
	v_mul_f32_e32 v24, 0x41000000, v24
	v_mul_f32_e32 v25, 0x41000000, v25
	v_mul_f32_e32 v26, 0x41000000, v26
	v_mul_f32_e32 v27, 0x41000000, v27
	v_mul_f32_e32 v28, 0x41000000, v28
	v_mul_f32_e32 v29, 0x41000000, v29
	v_mul_f32_e32 v30, 0x41000000, v30
	v_mul_f32_e32 v31, 0x41000000, v31
	v_cndmask_b32_e64 v24, v216, v24, s[26:27]
	v_cndmask_b32_e64 v25, v216, v25, s[36:37]
	v_cndmask_b32_e64 v26, v216, v26, s[10:11]
	v_cndmask_b32_e64 v27, v216, v27, s[0:1]
	v_cndmask_b32_e64 v28, v216, v28, s[6:7]
	v_cndmask_b32_e64 v29, v216, v29, s[8:9]
	v_cndmask_b32_e64 v30, v216, v30, s[16:17]
	v_cndmask_b32_e64 v31, v216, v31, s[20:21]
	global_load_dword v32, v[212:213], off offset:496
	global_load_dword v33, v[212:213], off offset:500
	global_load_dword v34, v[212:213], off offset:504
	global_load_dword v35, v[212:213], off offset:508
	global_load_dword v36, v[212:213], off offset:512
	global_load_dword v37, v[212:213], off offset:516
	global_load_dword v38, v[212:213], off offset:520
	global_load_dword v39, v[212:213], off offset:524
	global_load_dword v40, v[212:213], off offset:620
	global_load_dword v41, v[212:213], off offset:624
	global_load_dword v42, v[212:213], off offset:628
	global_load_dword v43, v[212:213], off offset:632
	global_load_dword v44, v[212:213], off offset:636
	global_load_dword v45, v[212:213], off offset:640
	global_load_dword v46, v[212:213], off offset:644
	global_load_dword v47, v[212:213], off offset:648
	global_load_dword v48, v[212:213], off offset:744
	global_load_dword v49, v[212:213], off offset:748
	global_load_dword v50, v[212:213], off offset:752
	global_load_dword v51, v[212:213], off offset:756
	global_load_dword v52, v[212:213], off offset:760
	global_load_dword v53, v[212:213], off offset:764
	global_load_dword v54, v[212:213], off offset:768
	global_load_dword v55, v[212:213], off offset:772
	global_load_dword v56, v[212:213], off offset:868
	global_load_dword v57, v[212:213], off offset:872
	global_load_dword v58, v[212:213], off offset:876
	global_load_dword v59, v[212:213], off offset:880
	global_load_dword v60, v[212:213], off offset:884
	global_load_dword v61, v[212:213], off offset:888
	global_load_dword v62, v[212:213], off offset:892
	global_load_dword v63, v[212:213], off offset:896
	s_waitcnt vmcnt(0)
	v_mul_f32_e32 v32, 0x41000000, v32
	v_mul_f32_e32 v33, 0x41000000, v33
	v_mul_f32_e32 v34, 0x41000000, v34
	v_mul_f32_e32 v35, 0x41000000, v35
	v_mul_f32_e32 v36, 0x41000000, v36
	v_mul_f32_e32 v37, 0x41000000, v37
	v_mul_f32_e32 v38, 0x41000000, v38
	v_mul_f32_e32 v39, 0x41000000, v39
	v_cndmask_b32_e64 v32, v216, v32, s[26:27]
	v_cndmask_b32_e64 v33, v216, v33, s[36:37]
	v_cndmask_b32_e64 v34, v216, v34, s[10:11]
	v_cndmask_b32_e64 v35, v216, v35, s[0:1]
	v_cndmask_b32_e64 v36, v216, v36, s[6:7]
	v_cndmask_b32_e64 v37, v216, v37, s[8:9]
	v_cndmask_b32_e64 v38, v216, v38, s[16:17]
	v_cndmask_b32_e64 v39, v216, v39, s[20:21]
	v_mul_f32_e32 v40, 0x41000000, v40
	v_mul_f32_e32 v41, 0x41000000, v41
	v_mul_f32_e32 v42, 0x41000000, v42
	v_mul_f32_e32 v43, 0x41000000, v43
	v_mul_f32_e32 v44, 0x41000000, v44
	v_mul_f32_e32 v45, 0x41000000, v45
	v_mul_f32_e32 v46, 0x41000000, v46
	v_mul_f32_e32 v47, 0x41000000, v47
	v_cndmask_b32_e64 v40, v216, v40, s[26:27]
	v_cndmask_b32_e64 v41, v216, v41, s[36:37]
	v_cndmask_b32_e64 v42, v216, v42, s[10:11]
	v_cndmask_b32_e64 v43, v216, v43, s[0:1]
	v_cndmask_b32_e64 v44, v216, v44, s[6:7]
	v_cndmask_b32_e64 v45, v216, v45, s[8:9]
	v_cndmask_b32_e64 v46, v216, v46, s[16:17]
	v_cndmask_b32_e64 v47, v216, v47, s[20:21]
	v_mul_f32_e32 v48, 0x41000000, v48
	v_mul_f32_e32 v49, 0x41000000, v49
	v_mul_f32_e32 v50, 0x41000000, v50
	v_mul_f32_e32 v51, 0x41000000, v51
	v_mul_f32_e32 v52, 0x41000000, v52
	v_mul_f32_e32 v53, 0x41000000, v53
	v_mul_f32_e32 v54, 0x41000000, v54
	v_mul_f32_e32 v55, 0x41000000, v55
	v_cndmask_b32_e64 v48, v216, v48, s[26:27]
	v_cndmask_b32_e64 v49, v216, v49, s[36:37]
	v_cndmask_b32_e64 v50, v216, v50, s[10:11]
	v_cndmask_b32_e64 v51, v216, v51, s[0:1]
	v_cndmask_b32_e64 v52, v216, v52, s[6:7]
	v_cndmask_b32_e64 v53, v216, v53, s[8:9]
	v_cndmask_b32_e64 v54, v216, v54, s[16:17]
	v_cndmask_b32_e64 v55, v216, v55, s[20:21]
	v_mul_f32_e32 v56, 0x41000000, v56
	v_mul_f32_e32 v57, 0x41000000, v57
	v_mul_f32_e32 v58, 0x41000000, v58
	v_mul_f32_e32 v59, 0x41000000, v59
	v_mul_f32_e32 v60, 0x41000000, v60
	v_mul_f32_e32 v61, 0x41000000, v61
	v_mul_f32_e32 v62, 0x41000000, v62
	v_mul_f32_e32 v63, 0x41000000, v63
	v_cndmask_b32_e64 v56, v216, v56, s[26:27]
	v_cndmask_b32_e64 v57, v216, v57, s[36:37]
	v_cndmask_b32_e64 v58, v216, v58, s[10:11]
	v_cndmask_b32_e64 v59, v216, v59, s[0:1]
	v_cndmask_b32_e64 v60, v216, v60, s[6:7]
	v_cndmask_b32_e64 v61, v216, v61, s[8:9]
	v_cndmask_b32_e64 v62, v216, v62, s[16:17]
	v_cndmask_b32_e64 v63, v216, v63, s[20:21]
	v_readlane_b32 s0, v136, 0
	v_readlane_b32 s1, v136, 1
	v_readlane_b32 s6, v136, 2
	v_readlane_b32 s7, v136, 3
	v_readlane_b32 s8, v136, 4
	v_readlane_b32 s9, v136, 5
	v_mfma_f32_16x16x32_bf16 v[0:3], v[138:141], v[128:131], v[0:3]
	v_mfma_f32_16x16x32_bf16 v[0:3], v[142:145], v[132:135], v[0:3]
	global_load_dwordx4 v[138:141], v209, s[22:23] offset:2048
	global_load_dwordx4 v[142:145], v209, s[22:23] offset:2112
	s_add_u32 s22, s22, 0x3800
	s_addc_u32 s23, s23, 0
	v_mfma_f32_16x16x32_bf16 v[4:7], v[146:149], v[128:131], v[4:7]
	v_mfma_f32_16x16x32_bf16 v[4:7], v[150:153], v[132:135], v[4:7]
	global_load_dwordx4 v[146:149], v209, s[22:23] offset:2048
	global_load_dwordx4 v[150:153], v209, s[22:23] offset:2112
	s_add_u32 s22, s22, 0x34800
	s_addc_u32 s23, s23, 0
	v_mfma_f32_16x16x32_bf16 v[8:11], v[154:157], v[128:131], v[8:11]
	v_mfma_f32_16x16x32_bf16 v[8:11], v[158:161], v[132:135], v[8:11]
	global_load_dwordx4 v[154:157], v209, s[22:23] offset:2048
	global_load_dwordx4 v[158:161], v209, s[22:23] offset:2112
	s_add_u32 s22, s22, 0x3800
	s_addc_u32 s23, s23, 0
	v_mfma_f32_16x16x32_bf16 v[12:15], v[162:165], v[128:131], v[12:15]
	v_mfma_f32_16x16x32_bf16 v[12:15], v[166:169], v[132:135], v[12:15]
	global_load_dwordx4 v[162:165], v209, s[22:23] offset:2048
	global_load_dwordx4 v[166:169], v209, s[22:23] offset:2112
	s_add_u32 s22, s22, 0x34800
	s_addc_u32 s23, s23, 0
	v_mfma_f32_16x16x32_bf16 v[16:19], v[170:173], v[128:131], v[16:19]
	v_mfma_f32_16x16x32_bf16 v[16:19], v[174:177], v[132:135], v[16:19]
	global_load_dwordx4 v[170:173], v209, s[22:23] offset:2048
	global_load_dwordx4 v[174:177], v209, s[22:23] offset:2112
	s_add_u32 s22, s22, 0x3800
	s_addc_u32 s23, s23, 0
	v_mfma_f32_16x16x32_bf16 v[20:23], v[178:181], v[128:131], v[20:23]
	v_mfma_f32_16x16x32_bf16 v[20:23], v[182:185], v[132:135], v[20:23]
	global_load_dwordx4 v[178:181], v209, s[22:23] offset:2048
	global_load_dwordx4 v[182:185], v209, s[22:23] offset:2112
	s_add_u32 s22, s22, 0x34800
	s_addc_u32 s23, s23, 0
	s_waitcnt vmcnt(11)
	v_mfma_f32_16x16x32_bf16 v[24:27], v[138:141], v[128:131], v[24:27]
	s_waitcnt vmcnt(10)
	v_mfma_f32_16x16x32_bf16 v[24:27], v[142:145], v[132:135], v[24:27]
	global_load_dwordx4 v[138:141], v209, s[22:23] offset:2048
	global_load_dwordx4 v[142:145], v209, s[22:23] offset:2112
	s_add_u32 s22, s22, 0x3800
	s_addc_u32 s23, s23, 0
	s_waitcnt vmcnt(11)
	v_mfma_f32_16x16x32_bf16 v[28:31], v[146:149], v[128:131], v[28:31]
	s_waitcnt vmcnt(10)
	v_mfma_f32_16x16x32_bf16 v[28:31], v[150:153], v[132:135], v[28:31]
	global_load_dwordx4 v[146:149], v209, s[22:23] offset:2048
	global_load_dwordx4 v[150:153], v209, s[22:23] offset:2112
	s_add_u32 s22, s22, 0x34800
	s_addc_u32 s23, s23, 0
	s_waitcnt vmcnt(11)
	v_mfma_f32_16x16x32_bf16 v[32:35], v[154:157], v[128:131], v[32:35]
	s_waitcnt vmcnt(10)
	v_mfma_f32_16x16x32_bf16 v[32:35], v[158:161], v[132:135], v[32:35]
	global_load_dwordx4 v[154:157], v209, s[22:23] offset:2048
	global_load_dwordx4 v[158:161], v209, s[22:23] offset:2112
	s_add_u32 s22, s22, 0x3800
	s_addc_u32 s23, s23, 0
	s_waitcnt vmcnt(11)
	v_mfma_f32_16x16x32_bf16 v[36:39], v[162:165], v[128:131], v[36:39]
	s_waitcnt vmcnt(10)
	v_mfma_f32_16x16x32_bf16 v[36:39], v[166:169], v[132:135], v[36:39]
	global_load_dwordx4 v[162:165], v209, s[22:23] offset:2048
	global_load_dwordx4 v[166:169], v209, s[22:23] offset:2112
	s_waitcnt vmcnt(11)
	v_mfma_f32_16x16x32_bf16 v[40:43], v[170:173], v[128:131], v[40:43]
	s_waitcnt vmcnt(10)
	v_mfma_f32_16x16x32_bf16 v[40:43], v[174:177], v[132:135], v[40:43]
	global_load_dwordx4 v[170:173], v209, s[24:25] offset:2048
	global_load_dwordx4 v[174:177], v209, s[24:25] offset:2112
	s_add_u32 s24, s24, 0x3800
	s_addc_u32 s25, s25, 0
	s_waitcnt vmcnt(11)
	v_mfma_f32_16x16x32_bf16 v[44:47], v[178:181], v[128:131], v[44:47]
	s_waitcnt vmcnt(10)
	v_mfma_f32_16x16x32_bf16 v[44:47], v[182:185], v[132:135], v[44:47]
	global_load_dwordx4 v[178:181], v209, s[24:25] offset:2048
	global_load_dwordx4 v[182:185], v209, s[24:25] offset:2112
	s_add_u32 s24, s24, 0x18800
	s_addc_u32 s25, s25, 0
	s_waitcnt vmcnt(11)
	v_mfma_f32_16x16x32_bf16 v[48:51], v[138:141], v[128:131], v[48:51]
	s_waitcnt vmcnt(10)
	v_mfma_f32_16x16x32_bf16 v[48:51], v[142:145], v[132:135], v[48:51]
	global_load_dwordx4 v[138:141], v209, s[24:25] offset:2048
	global_load_dwordx4 v[142:145], v209, s[24:25] offset:2112
	s_add_u32 s24, s24, 0x3800
	s_addc_u32 s25, s25, 0
	s_waitcnt vmcnt(11)
	v_mfma_f32_16x16x32_bf16 v[52:55], v[146:149], v[128:131], v[52:55]
	s_waitcnt vmcnt(10)
	v_mfma_f32_16x16x32_bf16 v[52:55], v[150:153], v[132:135], v[52:55]
	global_load_dwordx4 v[146:149], v209, s[24:25] offset:2048
	global_load_dwordx4 v[150:153], v209, s[24:25] offset:2112
	s_add_u32 s24, s24, 0x18800
	s_addc_u32 s25, s25, 0
	s_waitcnt vmcnt(11)
	v_mfma_f32_16x16x32_bf16 v[56:59], v[154:157], v[128:131], v[56:59]
	s_waitcnt vmcnt(10)
	v_mfma_f32_16x16x32_bf16 v[56:59], v[158:161], v[132:135], v[56:59]
	global_load_dwordx4 v[154:157], v209, s[24:25] offset:2048
	global_load_dwordx4 v[158:161], v209, s[24:25] offset:2112
	s_add_u32 s24, s24, 0x3800
	s_addc_u32 s25, s25, 0
	s_waitcnt vmcnt(11)
	v_mfma_f32_16x16x32_bf16 v[60:63], v[162:165], v[128:131], v[60:63]
	s_waitcnt vmcnt(10)
	v_mfma_f32_16x16x32_bf16 v[60:63], v[166:169], v[132:135], v[60:63]
	global_load_dwordx4 v[162:165], v209, s[24:25] offset:2048
	global_load_dwordx4 v[166:169], v209, s[24:25] offset:2112
	s_add_u32 s24, s24, 0x18800
	s_addc_u32 s25, s25, 0
	s_waitcnt vmcnt(11)
	v_mfma_f32_16x16x32_bf16 v[64:67], v[170:173], v[128:131], 0
	s_waitcnt vmcnt(10)
	v_mfma_f32_16x16x32_bf16 v[64:67], v[174:177], v[132:135], v[64:67]
	global_load_dwordx4 v[170:173], v209, s[24:25] offset:2048
	global_load_dwordx4 v[174:177], v209, s[24:25] offset:2112
	s_add_u32 s24, s24, 0x3800
	s_addc_u32 s25, s25, 0
	s_waitcnt vmcnt(11)
	v_mfma_f32_16x16x32_bf16 v[68:71], v[178:181], v[128:131], 0
	s_waitcnt vmcnt(10)
	v_mfma_f32_16x16x32_bf16 v[68:71], v[182:185], v[132:135], v[68:71]
	global_load_dwordx4 v[178:181], v209, s[24:25] offset:2048
	global_load_dwordx4 v[182:185], v209, s[24:25] offset:2112
	s_add_u32 s24, s24, 0x18800
	s_addc_u32 s25, s25, 0
	s_waitcnt vmcnt(11)
	v_mfma_f32_16x16x32_bf16 v[72:75], v[138:141], v[128:131], 0
	s_waitcnt vmcnt(10)
	v_mfma_f32_16x16x32_bf16 v[72:75], v[142:145], v[132:135], v[72:75]
	global_load_dwordx4 v[138:141], v209, s[24:25] offset:2048
	global_load_dwordx4 v[142:145], v209, s[24:25] offset:2112
	s_add_u32 s24, s24, 0x3800
	s_addc_u32 s25, s25, 0
	s_waitcnt vmcnt(11)
	v_mfma_f32_16x16x32_bf16 v[76:79], v[146:149], v[128:131], 0
	s_waitcnt vmcnt(10)
	v_mfma_f32_16x16x32_bf16 v[76:79], v[150:153], v[132:135], v[76:79]
	global_load_dwordx4 v[146:149], v209, s[24:25] offset:2048
	global_load_dwordx4 v[150:153], v209, s[24:25] offset:2112
	s_add_u32 s24, s24, 0x18800
	s_addc_u32 s25, s25, 0
	s_waitcnt vmcnt(11)
	v_mfma_f32_16x16x32_bf16 v[80:83], v[154:157], v[128:131], 0
	s_waitcnt vmcnt(10)
	v_mfma_f32_16x16x32_bf16 v[80:83], v[158:161], v[132:135], v[80:83]
	global_load_dwordx4 v[154:157], v209, s[24:25] offset:2048
	global_load_dwordx4 v[158:161], v209, s[24:25] offset:2112
	s_add_u32 s24, s24, 0x3800
	s_addc_u32 s25, s25, 0
	s_waitcnt vmcnt(11)
	v_mfma_f32_16x16x32_bf16 v[84:87], v[162:165], v[128:131], 0
	s_waitcnt vmcnt(10)
	v_mfma_f32_16x16x32_bf16 v[84:87], v[166:169], v[132:135], v[84:87]
	global_load_dwordx4 v[162:165], v209, s[24:25] offset:2048
	global_load_dwordx4 v[166:169], v209, s[24:25] offset:2112
	s_add_u32 s24, s24, 0x18800
	s_addc_u32 s25, s25, 0
	s_waitcnt vmcnt(11)
	v_mfma_f32_16x16x32_bf16 v[88:91], v[170:173], v[128:131], 0
	s_waitcnt vmcnt(10)
	v_mfma_f32_16x16x32_bf16 v[88:91], v[174:177], v[132:135], v[88:91]
	global_load_dwordx4 v[170:173], v209, s[24:25] offset:2048
	global_load_dwordx4 v[174:177], v209, s[24:25] offset:2112
	s_add_u32 s24, s24, 0x3800
	s_addc_u32 s25, s25, 0
	s_waitcnt vmcnt(11)
	v_mfma_f32_16x16x32_bf16 v[92:95], v[178:181], v[128:131], 0
	s_waitcnt vmcnt(10)
	v_mfma_f32_16x16x32_bf16 v[92:95], v[182:185], v[132:135], v[92:95]
	global_load_dwordx4 v[178:181], v209, s[24:25] offset:2048
	global_load_dwordx4 v[182:185], v209, s[24:25] offset:2112
	s_add_u32 s24, s24, 0x18800
	s_addc_u32 s25, s25, 0
	s_waitcnt vmcnt(11)
	v_mfma_f32_16x16x32_bf16 v[96:99], v[138:141], v[128:131], 0
	s_waitcnt vmcnt(10)
	v_mfma_f32_16x16x32_bf16 v[96:99], v[142:145], v[132:135], v[96:99]
	global_load_dwordx4 v[138:141], v209, s[24:25] offset:2048
	global_load_dwordx4 v[142:145], v209, s[24:25] offset:2112
	s_add_u32 s24, s24, 0x3800
	s_addc_u32 s25, s25, 0
	s_waitcnt vmcnt(11)
	v_mfma_f32_16x16x32_bf16 v[100:103], v[146:149], v[128:131], 0
	s_waitcnt vmcnt(10)
	v_mfma_f32_16x16x32_bf16 v[100:103], v[150:153], v[132:135], v[100:103]
	global_load_dwordx4 v[146:149], v209, s[24:25] offset:2048
	global_load_dwordx4 v[150:153], v209, s[24:25] offset:2112
	s_waitcnt vmcnt(11)
	v_mfma_f32_16x16x32_bf16 v[104:107], v[154:157], v[128:131], 0
	s_waitcnt vmcnt(10)
	v_mfma_f32_16x16x32_bf16 v[104:107], v[158:161], v[132:135], v[104:107]
	s_waitcnt vmcnt(9)
	v_mfma_f32_16x16x32_bf16 v[108:111], v[162:165], v[128:131], 0
	s_waitcnt vmcnt(8)
	v_mfma_f32_16x16x32_bf16 v[108:111], v[166:169], v[132:135], v[108:111]
	s_waitcnt vmcnt(7)
	v_mfma_f32_16x16x32_bf16 v[112:115], v[170:173], v[128:131], 0
	s_waitcnt vmcnt(6)
	v_mfma_f32_16x16x32_bf16 v[112:115], v[174:177], v[132:135], v[112:115]
	s_waitcnt vmcnt(5)
	v_mfma_f32_16x16x32_bf16 v[116:119], v[178:181], v[128:131], 0
	s_waitcnt vmcnt(4)
	v_mfma_f32_16x16x32_bf16 v[116:119], v[182:185], v[132:135], v[116:119]
	s_waitcnt vmcnt(3)
	v_mfma_f32_16x16x32_bf16 v[120:123], v[138:141], v[128:131], 0
	s_waitcnt vmcnt(2)
	v_mfma_f32_16x16x32_bf16 v[120:123], v[142:145], v[132:135], v[120:123]
	s_waitcnt vmcnt(1)
	v_mfma_f32_16x16x32_bf16 v[124:127], v[146:149], v[128:131], 0
	s_waitcnt vmcnt(0)
	v_mfma_f32_16x16x32_bf16 v[124:127], v[150:153], v[132:135], v[124:127]
	v_lshlrev_b32_e32 v210, 13, v206
	v_lshl_add_u32 v210, v207, 4, v210
	v_lshlrev_b32_e32 v211, 9, v206
	v_lshl_add_u32 v211, v207, 4, v211
	s_lshl_b32 s10, s8, 8
	s_lshl_b32 s11, s6, 6
	s_add_i32 s10, s10, s11
	s_lshl_b32 s11, s10, 13
	s_lshl_b32 s38, s7, 7
	s_add_i32 s11, s11, s38
	s_lshl_b32 s38, s9, 1
	s_add_i32 s11, s11, s38
	s_add_u32 s11, s11, 0x9a00000
	s_add_u32 s16, s4, s11
	s_addc_u32 s17, s5, 0
	s_add_u32 s18, s16, 0x20000
	s_addc_u32 s19, s17, 0
	s_add_u32 s20, s18, 0x20000
	s_addc_u32 s21, s19, 0
	s_add_u32 s22, s20, 0x20000
	s_addc_u32 s23, s21, 0
	s_lshl_b32 s11, s10, 9
	s_add_u32 s11, s11, 0xa200000
	s_add_u32 s24, s4, s11
	s_addc_u32 s25, s5, 0
	s_add_u32 s26, s24, 0x2000
	s_addc_u32 s27, s25, 0
	s_add_u32 s36, s26, 0x2000
	s_addc_u32 s37, s27, 0
	s_lshl_b32 s10, s8, 12
	s_lshl_b32 s11, s1, 6
	s_add_i32 s10, s10, s11
	s_lshl_b32 s11, s0, 4
	s_add_i32 s10, s10, s11
	s_addk_i32 s10, 0x400
	s_mul_i32 s10, s10, 0x600
	s_lshl_b32 s11, s6, 7
	s_add_i32 s10, s10, s11
	s_add_u32 s38, s10, 0xdf00400
	s_add_u32 s0, s36, 0x2000
	s_addc_u32 s1, s37, 0
	global_load_dwordx4 v[138:141], v210, s[16:17] offset:0
	global_load_dwordx4 v[142:145], v210, s[18:19] offset:0
	global_load_dwordx4 v[146:149], v210, s[20:21] offset:0
	global_load_dwordx4 v[150:153], v210, s[22:23] offset:0
	global_load_dwordx4 v[154:157], v210, s[16:17] offset:128
	global_load_dwordx4 v[158:161], v210, s[18:19] offset:128
	global_load_dwordx4 v[162:165], v210, s[20:21] offset:128
	global_load_dwordx4 v[166:169], v210, s[22:23] offset:128
	global_load_dwordx4 v[170:173], v210, s[16:17] offset:256
	global_load_dwordx4 v[174:177], v210, s[18:19] offset:256
	s_nop 7
	v_max3_f32 v214, v0, v1, v2
	v_max3_f32 v214, v214, v3, v4
	v_max3_f32 v214, v214, v5, v6
	v_max3_f32 v214, v214, v7, v8
	v_max3_f32 v214, v214, v9, v10
	v_max3_f32 v214, v214, v11, v12
	v_max3_f32 v214, v214, v13, v14
	v_max3_f32 v214, v214, v15, v16
	v_max3_f32 v214, v214, v17, v18
	v_max3_f32 v214, v214, v19, v20
	v_max3_f32 v214, v214, v21, v22
	v_max3_f32 v214, v214, v23, v24
	v_max3_f32 v214, v214, v25, v26
	v_max3_f32 v214, v214, v27, v28
	v_max3_f32 v214, v214, v29, v30
	v_max3_f32 v214, v214, v31, v32
	v_max3_f32 v214, v214, v33, v34
	v_max3_f32 v214, v214, v35, v36
	v_max3_f32 v214, v214, v37, v38
	v_max3_f32 v214, v214, v39, v40
	v_max3_f32 v214, v214, v41, v42
	v_max3_f32 v214, v214, v43, v44
	v_max3_f32 v214, v214, v45, v46
	v_max3_f32 v214, v214, v47, v48
	v_max3_f32 v214, v214, v49, v50
	v_max3_f32 v214, v214, v51, v52
	v_max3_f32 v214, v214, v53, v54
	v_max3_f32 v214, v214, v55, v56
	v_max3_f32 v214, v214, v57, v58
	v_max3_f32 v214, v214, v59, v60
	v_max3_f32 v214, v214, v61, v62
	v_max3_f32 v214, v214, v63, v64
	v_max3_f32 v214, v214, v65, v66
	v_max3_f32 v214, v214, v67, v68
	v_max3_f32 v214, v214, v69, v70
	v_max3_f32 v214, v214, v71, v72
	v_max3_f32 v214, v214, v73, v74
	v_max3_f32 v214, v214, v75, v76
	v_max3_f32 v214, v214, v77, v78
	v_max3_f32 v214, v214, v79, v80
	v_max3_f32 v214, v214, v81, v82
	v_max3_f32 v214, v214, v83, v84
	v_max3_f32 v214, v214, v85, v86
	v_max3_f32 v214, v214, v87, v88
	v_max3_f32 v214, v214, v89, v90
	v_max3_f32 v214, v214, v91, v92
	v_max3_f32 v214, v214, v93, v94
	v_max3_f32 v214, v214, v95, v96
	v_max3_f32 v214, v214, v97, v98
	v_max3_f32 v214, v214, v99, v100
	v_max3_f32 v214, v214, v101, v102
	v_max3_f32 v214, v214, v103, v104
	v_max3_f32 v214, v214, v105, v106
	v_max3_f32 v214, v214, v107, v108
	v_max3_f32 v214, v214, v109, v110
	v_max3_f32 v214, v214, v111, v112
	v_max3_f32 v214, v214, v113, v114
	v_max3_f32 v214, v214, v115, v116
	v_max3_f32 v214, v214, v117, v118
	v_max3_f32 v214, v214, v119, v120
	v_max3_f32 v214, v214, v121, v122
	v_max3_f32 v214, v214, v123, v124
	v_max3_f32 v214, v214, v125, v126
	v_max_f32_e32 v214, v214, v127
	v_xor_b32_e32 v215, 16, v205
	v_lshlrev_b32_e32 v215, 2, v215
	v_xor_b32_e32 v216, 32, v205
	v_lshlrev_b32_e32 v216, 2, v216
	ds_bpermute_b32 v136, v215, v214
	s_waitcnt lgkmcnt(0)
	v_max_f32_e32 v214, v214, v136
	ds_bpermute_b32 v136, v216, v214
	s_waitcnt lgkmcnt(0)
	v_max_f32_e32 v214, v214, v136
	v_mul_f32_e32 v214, 0xbe38aa3b, v214
	s_mov_b32 s10, 0x3e38aa3b
	v_mov_b32_e32 v212, 0
	v_mov_b32_e32 v213, 0
	v_fma_f32 v0, v0, s10, v214
	v_fma_f32 v1, v1, s10, v214
	v_fma_f32 v2, v2, s10, v214
	v_fma_f32 v3, v3, s10, v214
	v_fma_f32 v4, v4, s10, v214
	v_fma_f32 v5, v5, s10, v214
	v_fma_f32 v6, v6, s10, v214
	v_fma_f32 v7, v7, s10, v214
	v_exp_f32_e32 v0, v0
	v_exp_f32_e32 v1, v1
	v_exp_f32_e32 v2, v2
	v_exp_f32_e32 v3, v3
	v_exp_f32_e32 v4, v4
	v_exp_f32_e32 v5, v5
	v_exp_f32_e32 v6, v6
	v_exp_f32_e32 v7, v7
	s_nop 0
	v_add_f32_e32 v212, v212, v0
	v_add_f32_e32 v213, v213, v1
	v_add_f32_e32 v212, v212, v2
	v_add_f32_e32 v213, v213, v3
	v_add_f32_e32 v212, v212, v4
	v_add_f32_e32 v213, v213, v5
	v_add_f32_e32 v212, v212, v6
	v_add_f32_e32 v213, v213, v7
	v_bfe_u32 v136, v0, 16, 1
	v_bfe_u32 v208, v1, 16, 1
	v_add3_u32 v136, v0, v136, s77
	v_add3_u32 v208, v1, v208, s77
	v_lshrrev_b32_e32 v136, 16, v136
	v_and_or_b32 v0, v208, s35, v136
	v_bfe_u32 v136, v2, 16, 1
	v_bfe_u32 v208, v3, 16, 1
	v_add3_u32 v136, v2, v136, s77
	v_add3_u32 v208, v3, v208, s77
	v_lshrrev_b32_e32 v136, 16, v136
	v_and_or_b32 v1, v208, s35, v136
	v_bfe_u32 v136, v4, 16, 1
	v_bfe_u32 v208, v5, 16, 1
	v_add3_u32 v136, v4, v136, s77
	v_add3_u32 v208, v5, v208, s77
	v_lshrrev_b32_e32 v136, 16, v136
	v_and_or_b32 v2, v208, s35, v136
	v_bfe_u32 v136, v6, 16, 1
	v_bfe_u32 v208, v7, 16, 1
	v_add3_u32 v136, v6, v136, s77
	v_add3_u32 v208, v7, v208, s77
	v_lshrrev_b32_e32 v136, 16, v136
	v_and_or_b32 v3, v208, s35, v136
	v_fma_f32 v8, v8, s10, v214
	v_fma_f32 v9, v9, s10, v214
	v_fma_f32 v10, v10, s10, v214
	v_fma_f32 v11, v11, s10, v214
	v_fma_f32 v12, v12, s10, v214
	v_fma_f32 v13, v13, s10, v214
	v_fma_f32 v14, v14, s10, v214
	v_fma_f32 v15, v15, s10, v214
	v_exp_f32_e32 v8, v8
	v_exp_f32_e32 v9, v9
	v_exp_f32_e32 v10, v10
	v_exp_f32_e32 v11, v11
	v_exp_f32_e32 v12, v12
	v_exp_f32_e32 v13, v13
	v_exp_f32_e32 v14, v14
	v_exp_f32_e32 v15, v15
	s_nop 0
	v_add_f32_e32 v212, v212, v8
	v_add_f32_e32 v213, v213, v9
	v_add_f32_e32 v212, v212, v10
	v_add_f32_e32 v213, v213, v11
	v_add_f32_e32 v212, v212, v12
	v_add_f32_e32 v213, v213, v13
	v_add_f32_e32 v212, v212, v14
	v_add_f32_e32 v213, v213, v15
	v_bfe_u32 v136, v8, 16, 1
	v_bfe_u32 v208, v9, 16, 1
	v_add3_u32 v136, v8, v136, s77
	v_add3_u32 v208, v9, v208, s77
	v_lshrrev_b32_e32 v136, 16, v136
	v_and_or_b32 v8, v208, s35, v136
	v_bfe_u32 v136, v10, 16, 1
	v_bfe_u32 v208, v11, 16, 1
	v_add3_u32 v136, v10, v136, s77
	v_add3_u32 v208, v11, v208, s77
	v_lshrrev_b32_e32 v136, 16, v136
	v_and_or_b32 v9, v208, s35, v136
	v_bfe_u32 v136, v12, 16, 1
	v_bfe_u32 v208, v13, 16, 1
	v_add3_u32 v136, v12, v136, s77
	v_add3_u32 v208, v13, v208, s77
	v_lshrrev_b32_e32 v136, 16, v136
	v_and_or_b32 v10, v208, s35, v136
	v_bfe_u32 v136, v14, 16, 1
	v_bfe_u32 v208, v15, 16, 1
	v_add3_u32 v136, v14, v136, s77
	v_add3_u32 v208, v15, v208, s77
	v_lshrrev_b32_e32 v136, 16, v136
	v_and_or_b32 v11, v208, s35, v136
	v_fma_f32 v16, v16, s10, v214
	v_fma_f32 v17, v17, s10, v214
	v_fma_f32 v18, v18, s10, v214
	v_fma_f32 v19, v19, s10, v214
	v_fma_f32 v20, v20, s10, v214
	v_fma_f32 v21, v21, s10, v214
	v_fma_f32 v22, v22, s10, v214
	v_fma_f32 v23, v23, s10, v214
	v_exp_f32_e32 v16, v16
	v_exp_f32_e32 v17, v17
	v_exp_f32_e32 v18, v18
	v_exp_f32_e32 v19, v19
	v_exp_f32_e32 v20, v20
	v_exp_f32_e32 v21, v21
	v_exp_f32_e32 v22, v22
	v_exp_f32_e32 v23, v23
	s_nop 0
	v_add_f32_e32 v212, v212, v16
	v_add_f32_e32 v213, v213, v17
	v_add_f32_e32 v212, v212, v18
	v_add_f32_e32 v213, v213, v19
	v_add_f32_e32 v212, v212, v20
	v_add_f32_e32 v213, v213, v21
	v_add_f32_e32 v212, v212, v22
	v_add_f32_e32 v213, v213, v23
	v_bfe_u32 v136, v16, 16, 1
	v_bfe_u32 v208, v17, 16, 1
	v_add3_u32 v136, v16, v136, s77
	v_add3_u32 v208, v17, v208, s77
	v_lshrrev_b32_e32 v136, 16, v136
	v_and_or_b32 v16, v208, s35, v136
	v_bfe_u32 v136, v18, 16, 1
	v_bfe_u32 v208, v19, 16, 1
	v_add3_u32 v136, v18, v136, s77
	v_add3_u32 v208, v19, v208, s77
	v_lshrrev_b32_e32 v136, 16, v136
	v_and_or_b32 v17, v208, s35, v136
	v_bfe_u32 v136, v20, 16, 1
	v_bfe_u32 v208, v21, 16, 1
	v_add3_u32 v136, v20, v136, s77
	v_add3_u32 v208, v21, v208, s77
	v_lshrrev_b32_e32 v136, 16, v136
	v_and_or_b32 v18, v208, s35, v136
	v_bfe_u32 v136, v22, 16, 1
	v_bfe_u32 v208, v23, 16, 1
	v_add3_u32 v136, v22, v136, s77
	v_add3_u32 v208, v23, v208, s77
	v_lshrrev_b32_e32 v136, 16, v136
	v_and_or_b32 v19, v208, s35, v136
	v_fma_f32 v24, v24, s10, v214
	v_fma_f32 v25, v25, s10, v214
	v_fma_f32 v26, v26, s10, v214
	v_fma_f32 v27, v27, s10, v214
	v_fma_f32 v28, v28, s10, v214
	v_fma_f32 v29, v29, s10, v214
	v_fma_f32 v30, v30, s10, v214
	v_fma_f32 v31, v31, s10, v214
	v_exp_f32_e32 v24, v24
	v_exp_f32_e32 v25, v25
	v_exp_f32_e32 v26, v26
	v_exp_f32_e32 v27, v27
	v_exp_f32_e32 v28, v28
	v_exp_f32_e32 v29, v29
	v_exp_f32_e32 v30, v30
	v_exp_f32_e32 v31, v31
	s_nop 0
	v_add_f32_e32 v212, v212, v24
	v_add_f32_e32 v213, v213, v25
	v_add_f32_e32 v212, v212, v26
	v_add_f32_e32 v213, v213, v27
	v_add_f32_e32 v212, v212, v28
	v_add_f32_e32 v213, v213, v29
	v_add_f32_e32 v212, v212, v30
	v_add_f32_e32 v213, v213, v31
	v_bfe_u32 v136, v24, 16, 1
	v_bfe_u32 v208, v25, 16, 1
	v_add3_u32 v136, v24, v136, s77
	v_add3_u32 v208, v25, v208, s77
	v_lshrrev_b32_e32 v136, 16, v136
	v_and_or_b32 v24, v208, s35, v136
	v_bfe_u32 v136, v26, 16, 1
	v_bfe_u32 v208, v27, 16, 1
	v_add3_u32 v136, v26, v136, s77
	v_add3_u32 v208, v27, v208, s77
	v_lshrrev_b32_e32 v136, 16, v136
	v_and_or_b32 v25, v208, s35, v136
	v_bfe_u32 v136, v28, 16, 1
	v_bfe_u32 v208, v29, 16, 1
	v_add3_u32 v136, v28, v136, s77
	v_add3_u32 v208, v29, v208, s77
	v_lshrrev_b32_e32 v136, 16, v136
	v_and_or_b32 v26, v208, s35, v136
	v_bfe_u32 v136, v30, 16, 1
	v_bfe_u32 v208, v31, 16, 1
	v_add3_u32 v136, v30, v136, s77
	v_add3_u32 v208, v31, v208, s77
	v_lshrrev_b32_e32 v136, 16, v136
	v_and_or_b32 v27, v208, s35, v136
	v_fma_f32 v32, v32, s10, v214
	v_fma_f32 v33, v33, s10, v214
	v_fma_f32 v34, v34, s10, v214
	v_fma_f32 v35, v35, s10, v214
	v_fma_f32 v36, v36, s10, v214
	v_fma_f32 v37, v37, s10, v214
	v_fma_f32 v38, v38, s10, v214
	v_fma_f32 v39, v39, s10, v214
	v_exp_f32_e32 v32, v32
	v_exp_f32_e32 v33, v33
	v_exp_f32_e32 v34, v34
	v_exp_f32_e32 v35, v35
	v_exp_f32_e32 v36, v36
	v_exp_f32_e32 v37, v37
	v_exp_f32_e32 v38, v38
	v_exp_f32_e32 v39, v39
	s_nop 0
	v_add_f32_e32 v212, v212, v32
	v_add_f32_e32 v213, v213, v33
	v_add_f32_e32 v212, v212, v34
	v_add_f32_e32 v213, v213, v35
	v_add_f32_e32 v212, v212, v36
	v_add_f32_e32 v213, v213, v37
	v_add_f32_e32 v212, v212, v38
	v_add_f32_e32 v213, v213, v39
	v_bfe_u32 v136, v32, 16, 1
	v_bfe_u32 v208, v33, 16, 1
	v_add3_u32 v136, v32, v136, s77
	v_add3_u32 v208, v33, v208, s77
	v_lshrrev_b32_e32 v136, 16, v136
	v_and_or_b32 v32, v208, s35, v136
	v_bfe_u32 v136, v34, 16, 1
	v_bfe_u32 v208, v35, 16, 1
	v_add3_u32 v136, v34, v136, s77
	v_add3_u32 v208, v35, v208, s77
	v_lshrrev_b32_e32 v136, 16, v136
	v_and_or_b32 v33, v208, s35, v136
	v_bfe_u32 v136, v36, 16, 1
	v_bfe_u32 v208, v37, 16, 1
	v_add3_u32 v136, v36, v136, s77
	v_add3_u32 v208, v37, v208, s77
	v_lshrrev_b32_e32 v136, 16, v136
	v_and_or_b32 v34, v208, s35, v136
	v_bfe_u32 v136, v38, 16, 1
	v_bfe_u32 v208, v39, 16, 1
	v_add3_u32 v136, v38, v136, s77
	v_add3_u32 v208, v39, v208, s77
	v_lshrrev_b32_e32 v136, 16, v136
	v_and_or_b32 v35, v208, s35, v136
	v_fma_f32 v40, v40, s10, v214
	v_fma_f32 v41, v41, s10, v214
	v_fma_f32 v42, v42, s10, v214
	v_fma_f32 v43, v43, s10, v214
	v_fma_f32 v44, v44, s10, v214
	v_fma_f32 v45, v45, s10, v214
	v_fma_f32 v46, v46, s10, v214
	v_fma_f32 v47, v47, s10, v214
	v_exp_f32_e32 v40, v40
	v_exp_f32_e32 v41, v41
	v_exp_f32_e32 v42, v42
	v_exp_f32_e32 v43, v43
	v_exp_f32_e32 v44, v44
	v_exp_f32_e32 v45, v45
	v_exp_f32_e32 v46, v46
	v_exp_f32_e32 v47, v47
	s_nop 0
	v_add_f32_e32 v212, v212, v40
	v_add_f32_e32 v213, v213, v41
	v_add_f32_e32 v212, v212, v42
	v_add_f32_e32 v213, v213, v43
	v_add_f32_e32 v212, v212, v44
	v_add_f32_e32 v213, v213, v45
	v_add_f32_e32 v212, v212, v46
	v_add_f32_e32 v213, v213, v47
	v_bfe_u32 v136, v40, 16, 1
	v_bfe_u32 v208, v41, 16, 1
	v_add3_u32 v136, v40, v136, s77
	v_add3_u32 v208, v41, v208, s77
	v_lshrrev_b32_e32 v136, 16, v136
	v_and_or_b32 v40, v208, s35, v136
	v_bfe_u32 v136, v42, 16, 1
	v_bfe_u32 v208, v43, 16, 1
	v_add3_u32 v136, v42, v136, s77
	v_add3_u32 v208, v43, v208, s77
	v_lshrrev_b32_e32 v136, 16, v136
	v_and_or_b32 v41, v208, s35, v136
	v_bfe_u32 v136, v44, 16, 1
	v_bfe_u32 v208, v45, 16, 1
	v_add3_u32 v136, v44, v136, s77
	v_add3_u32 v208, v45, v208, s77
	v_lshrrev_b32_e32 v136, 16, v136
	v_and_or_b32 v42, v208, s35, v136
	v_bfe_u32 v136, v46, 16, 1
	v_bfe_u32 v208, v47, 16, 1
	v_add3_u32 v136, v46, v136, s77
	v_add3_u32 v208, v47, v208, s77
	v_lshrrev_b32_e32 v136, 16, v136
	v_and_or_b32 v43, v208, s35, v136
	v_fma_f32 v48, v48, s10, v214
	v_fma_f32 v49, v49, s10, v214
	v_fma_f32 v50, v50, s10, v214
	v_fma_f32 v51, v51, s10, v214
	v_fma_f32 v52, v52, s10, v214
	v_fma_f32 v53, v53, s10, v214
	v_fma_f32 v54, v54, s10, v214
	v_fma_f32 v55, v55, s10, v214
	v_exp_f32_e32 v48, v48
	v_exp_f32_e32 v49, v49
	v_exp_f32_e32 v50, v50
	v_exp_f32_e32 v51, v51
	v_exp_f32_e32 v52, v52
	v_exp_f32_e32 v53, v53
	v_exp_f32_e32 v54, v54
	v_exp_f32_e32 v55, v55
	s_nop 0
	v_add_f32_e32 v212, v212, v48
	v_add_f32_e32 v213, v213, v49
	v_add_f32_e32 v212, v212, v50
	v_add_f32_e32 v213, v213, v51
	v_add_f32_e32 v212, v212, v52
	v_add_f32_e32 v213, v213, v53
	v_add_f32_e32 v212, v212, v54
	v_add_f32_e32 v213, v213, v55
	v_bfe_u32 v136, v48, 16, 1
	v_bfe_u32 v208, v49, 16, 1
	v_add3_u32 v136, v48, v136, s77
	v_add3_u32 v208, v49, v208, s77
	v_lshrrev_b32_e32 v136, 16, v136
	v_and_or_b32 v48, v208, s35, v136
	v_bfe_u32 v136, v50, 16, 1
	v_bfe_u32 v208, v51, 16, 1
	v_add3_u32 v136, v50, v136, s77
	v_add3_u32 v208, v51, v208, s77
	v_lshrrev_b32_e32 v136, 16, v136
	v_and_or_b32 v49, v208, s35, v136
	v_bfe_u32 v136, v52, 16, 1
	v_bfe_u32 v208, v53, 16, 1
	v_add3_u32 v136, v52, v136, s77
	v_add3_u32 v208, v53, v208, s77
	v_lshrrev_b32_e32 v136, 16, v136
	v_and_or_b32 v50, v208, s35, v136
	v_bfe_u32 v136, v54, 16, 1
	v_bfe_u32 v208, v55, 16, 1
	v_add3_u32 v136, v54, v136, s77
	v_add3_u32 v208, v55, v208, s77
	v_lshrrev_b32_e32 v136, 16, v136
	v_and_or_b32 v51, v208, s35, v136
	v_fma_f32 v56, v56, s10, v214
	v_fma_f32 v57, v57, s10, v214
	v_fma_f32 v58, v58, s10, v214
	v_fma_f32 v59, v59, s10, v214
	v_fma_f32 v60, v60, s10, v214
	v_fma_f32 v61, v61, s10, v214
	v_fma_f32 v62, v62, s10, v214
	v_fma_f32 v63, v63, s10, v214
	v_exp_f32_e32 v56, v56
	v_exp_f32_e32 v57, v57
	v_exp_f32_e32 v58, v58
	v_exp_f32_e32 v59, v59
	v_exp_f32_e32 v60, v60
	v_exp_f32_e32 v61, v61
	v_exp_f32_e32 v62, v62
	v_exp_f32_e32 v63, v63
	s_nop 0
	v_add_f32_e32 v212, v212, v56
	v_add_f32_e32 v213, v213, v57
	v_add_f32_e32 v212, v212, v58
	v_add_f32_e32 v213, v213, v59
	v_add_f32_e32 v212, v212, v60
	v_add_f32_e32 v213, v213, v61
	v_add_f32_e32 v212, v212, v62
	v_add_f32_e32 v213, v213, v63
	v_bfe_u32 v136, v56, 16, 1
	v_bfe_u32 v208, v57, 16, 1
	v_add3_u32 v136, v56, v136, s77
	v_add3_u32 v208, v57, v208, s77
	v_lshrrev_b32_e32 v136, 16, v136
	v_and_or_b32 v56, v208, s35, v136
	v_bfe_u32 v136, v58, 16, 1
	v_bfe_u32 v208, v59, 16, 1
	v_add3_u32 v136, v58, v136, s77
	v_add3_u32 v208, v59, v208, s77
	v_lshrrev_b32_e32 v136, 16, v136
	v_and_or_b32 v57, v208, s35, v136
	v_bfe_u32 v136, v60, 16, 1
	v_bfe_u32 v208, v61, 16, 1
	v_add3_u32 v136, v60, v136, s77
	v_add3_u32 v208, v61, v208, s77
	v_lshrrev_b32_e32 v136, 16, v136
	v_and_or_b32 v58, v208, s35, v136
	v_bfe_u32 v136, v62, 16, 1
	v_bfe_u32 v208, v63, 16, 1
	v_add3_u32 v136, v62, v136, s77
	v_add3_u32 v208, v63, v208, s77
	v_lshrrev_b32_e32 v136, 16, v136
	v_and_or_b32 v59, v208, s35, v136
	v_fma_f32 v64, v64, s10, v214
	v_fma_f32 v65, v65, s10, v214
	v_fma_f32 v66, v66, s10, v214
	v_fma_f32 v67, v67, s10, v214
	v_fma_f32 v68, v68, s10, v214
	v_fma_f32 v69, v69, s10, v214
	v_fma_f32 v70, v70, s10, v214
	v_fma_f32 v71, v71, s10, v214
	v_exp_f32_e32 v64, v64
	v_exp_f32_e32 v65, v65
	v_exp_f32_e32 v66, v66
	v_exp_f32_e32 v67, v67
	v_exp_f32_e32 v68, v68
	v_exp_f32_e32 v69, v69
	v_exp_f32_e32 v70, v70
	v_exp_f32_e32 v71, v71
	s_nop 0
	v_add_f32_e32 v212, v212, v64
	v_add_f32_e32 v213, v213, v65
	v_add_f32_e32 v212, v212, v66
	v_add_f32_e32 v213, v213, v67
	v_add_f32_e32 v212, v212, v68
	v_add_f32_e32 v213, v213, v69
	v_add_f32_e32 v212, v212, v70
	v_add_f32_e32 v213, v213, v71
	v_bfe_u32 v136, v64, 16, 1
	v_bfe_u32 v208, v65, 16, 1
	v_add3_u32 v136, v64, v136, s77
	v_add3_u32 v208, v65, v208, s77
	v_lshrrev_b32_e32 v136, 16, v136
	v_and_or_b32 v64, v208, s35, v136
	v_bfe_u32 v136, v66, 16, 1
	v_bfe_u32 v208, v67, 16, 1
	v_add3_u32 v136, v66, v136, s77
	v_add3_u32 v208, v67, v208, s77
	v_lshrrev_b32_e32 v136, 16, v136
	v_and_or_b32 v65, v208, s35, v136
	v_bfe_u32 v136, v68, 16, 1
	v_bfe_u32 v208, v69, 16, 1
	v_add3_u32 v136, v68, v136, s77
	v_add3_u32 v208, v69, v208, s77
	v_lshrrev_b32_e32 v136, 16, v136
	v_and_or_b32 v66, v208, s35, v136
	v_bfe_u32 v136, v70, 16, 1
	v_bfe_u32 v208, v71, 16, 1
	v_add3_u32 v136, v70, v136, s77
	v_add3_u32 v208, v71, v208, s77
	v_lshrrev_b32_e32 v136, 16, v136
	v_and_or_b32 v67, v208, s35, v136
	v_fma_f32 v72, v72, s10, v214
	v_fma_f32 v73, v73, s10, v214
	v_fma_f32 v74, v74, s10, v214
	v_fma_f32 v75, v75, s10, v214
	v_fma_f32 v76, v76, s10, v214
	v_fma_f32 v77, v77, s10, v214
	v_fma_f32 v78, v78, s10, v214
	v_fma_f32 v79, v79, s10, v214
	v_exp_f32_e32 v72, v72
	v_exp_f32_e32 v73, v73
	v_exp_f32_e32 v74, v74
	v_exp_f32_e32 v75, v75
	v_exp_f32_e32 v76, v76
	v_exp_f32_e32 v77, v77
	v_exp_f32_e32 v78, v78
	v_exp_f32_e32 v79, v79
	s_nop 0
	v_add_f32_e32 v212, v212, v72
	v_add_f32_e32 v213, v213, v73
	v_add_f32_e32 v212, v212, v74
	v_add_f32_e32 v213, v213, v75
	v_add_f32_e32 v212, v212, v76
	v_add_f32_e32 v213, v213, v77
	v_add_f32_e32 v212, v212, v78
	v_add_f32_e32 v213, v213, v79
	v_bfe_u32 v136, v72, 16, 1
	v_bfe_u32 v208, v73, 16, 1
	v_add3_u32 v136, v72, v136, s77
	v_add3_u32 v208, v73, v208, s77
	v_lshrrev_b32_e32 v136, 16, v136
	v_and_or_b32 v72, v208, s35, v136
	v_bfe_u32 v136, v74, 16, 1
	v_bfe_u32 v208, v75, 16, 1
	v_add3_u32 v136, v74, v136, s77
	v_add3_u32 v208, v75, v208, s77
	v_lshrrev_b32_e32 v136, 16, v136
	v_and_or_b32 v73, v208, s35, v136
	v_bfe_u32 v136, v76, 16, 1
	v_bfe_u32 v208, v77, 16, 1
	v_add3_u32 v136, v76, v136, s77
	v_add3_u32 v208, v77, v208, s77
	v_lshrrev_b32_e32 v136, 16, v136
	v_and_or_b32 v74, v208, s35, v136
	v_bfe_u32 v136, v78, 16, 1
	v_bfe_u32 v208, v79, 16, 1
	v_add3_u32 v136, v78, v136, s77
	v_add3_u32 v208, v79, v208, s77
	v_lshrrev_b32_e32 v136, 16, v136
	v_and_or_b32 v75, v208, s35, v136
	v_fma_f32 v80, v80, s10, v214
	v_fma_f32 v81, v81, s10, v214
	v_fma_f32 v82, v82, s10, v214
	v_fma_f32 v83, v83, s10, v214
	v_fma_f32 v84, v84, s10, v214
	v_fma_f32 v85, v85, s10, v214
	v_fma_f32 v86, v86, s10, v214
	v_fma_f32 v87, v87, s10, v214
	v_exp_f32_e32 v80, v80
	v_exp_f32_e32 v81, v81
	v_exp_f32_e32 v82, v82
	v_exp_f32_e32 v83, v83
	v_exp_f32_e32 v84, v84
	v_exp_f32_e32 v85, v85
	v_exp_f32_e32 v86, v86
	v_exp_f32_e32 v87, v87
	s_nop 0
	v_add_f32_e32 v212, v212, v80
	v_add_f32_e32 v213, v213, v81
	v_add_f32_e32 v212, v212, v82
	v_add_f32_e32 v213, v213, v83
	v_add_f32_e32 v212, v212, v84
	v_add_f32_e32 v213, v213, v85
	v_add_f32_e32 v212, v212, v86
	v_add_f32_e32 v213, v213, v87
	v_bfe_u32 v136, v80, 16, 1
	v_bfe_u32 v208, v81, 16, 1
	v_add3_u32 v136, v80, v136, s77
	v_add3_u32 v208, v81, v208, s77
	v_lshrrev_b32_e32 v136, 16, v136
	v_and_or_b32 v80, v208, s35, v136
	v_bfe_u32 v136, v82, 16, 1
	v_bfe_u32 v208, v83, 16, 1
	v_add3_u32 v136, v82, v136, s77
	v_add3_u32 v208, v83, v208, s77
	v_lshrrev_b32_e32 v136, 16, v136
	v_and_or_b32 v81, v208, s35, v136
	v_bfe_u32 v136, v84, 16, 1
	v_bfe_u32 v208, v85, 16, 1
	v_add3_u32 v136, v84, v136, s77
	v_add3_u32 v208, v85, v208, s77
	v_lshrrev_b32_e32 v136, 16, v136
	v_and_or_b32 v82, v208, s35, v136
	v_bfe_u32 v136, v86, 16, 1
	v_bfe_u32 v208, v87, 16, 1
	v_add3_u32 v136, v86, v136, s77
	v_add3_u32 v208, v87, v208, s77
	v_lshrrev_b32_e32 v136, 16, v136
	v_and_or_b32 v83, v208, s35, v136
	v_fma_f32 v88, v88, s10, v214
	v_fma_f32 v89, v89, s10, v214
	v_fma_f32 v90, v90, s10, v214
	v_fma_f32 v91, v91, s10, v214
	v_fma_f32 v92, v92, s10, v214
	v_fma_f32 v93, v93, s10, v214
	v_fma_f32 v94, v94, s10, v214
	v_fma_f32 v95, v95, s10, v214
	v_exp_f32_e32 v88, v88
	v_exp_f32_e32 v89, v89
	v_exp_f32_e32 v90, v90
	v_exp_f32_e32 v91, v91
	v_exp_f32_e32 v92, v92
	v_exp_f32_e32 v93, v93
	v_exp_f32_e32 v94, v94
	v_exp_f32_e32 v95, v95
	s_nop 0
	v_add_f32_e32 v212, v212, v88
	v_add_f32_e32 v213, v213, v89
	v_add_f32_e32 v212, v212, v90
	v_add_f32_e32 v213, v213, v91
	v_add_f32_e32 v212, v212, v92
	v_add_f32_e32 v213, v213, v93
	v_add_f32_e32 v212, v212, v94
	v_add_f32_e32 v213, v213, v95
	v_bfe_u32 v136, v88, 16, 1
	v_bfe_u32 v208, v89, 16, 1
	v_add3_u32 v136, v88, v136, s77
	v_add3_u32 v208, v89, v208, s77
	v_lshrrev_b32_e32 v136, 16, v136
	v_and_or_b32 v88, v208, s35, v136
	v_bfe_u32 v136, v90, 16, 1
	v_bfe_u32 v208, v91, 16, 1
	v_add3_u32 v136, v90, v136, s77
	v_add3_u32 v208, v91, v208, s77
	v_lshrrev_b32_e32 v136, 16, v136
	v_and_or_b32 v89, v208, s35, v136
	v_bfe_u32 v136, v92, 16, 1
	v_bfe_u32 v208, v93, 16, 1
	v_add3_u32 v136, v92, v136, s77
	v_add3_u32 v208, v93, v208, s77
	v_lshrrev_b32_e32 v136, 16, v136
	v_and_or_b32 v90, v208, s35, v136
	v_bfe_u32 v136, v94, 16, 1
	v_bfe_u32 v208, v95, 16, 1
	v_add3_u32 v136, v94, v136, s77
	v_add3_u32 v208, v95, v208, s77
	v_lshrrev_b32_e32 v136, 16, v136
	v_and_or_b32 v91, v208, s35, v136
	v_fma_f32 v96, v96, s10, v214
	v_fma_f32 v97, v97, s10, v214
	v_fma_f32 v98, v98, s10, v214
	v_fma_f32 v99, v99, s10, v214
	v_fma_f32 v100, v100, s10, v214
	v_fma_f32 v101, v101, s10, v214
	v_fma_f32 v102, v102, s10, v214
	v_fma_f32 v103, v103, s10, v214
	v_exp_f32_e32 v96, v96
	v_exp_f32_e32 v97, v97
	v_exp_f32_e32 v98, v98
	v_exp_f32_e32 v99, v99
	v_exp_f32_e32 v100, v100
	v_exp_f32_e32 v101, v101
	v_exp_f32_e32 v102, v102
	v_exp_f32_e32 v103, v103
	s_nop 0
	v_add_f32_e32 v212, v212, v96
	v_add_f32_e32 v213, v213, v97
	v_add_f32_e32 v212, v212, v98
	v_add_f32_e32 v213, v213, v99
	v_add_f32_e32 v212, v212, v100
	v_add_f32_e32 v213, v213, v101
	v_add_f32_e32 v212, v212, v102
	v_add_f32_e32 v213, v213, v103
	v_bfe_u32 v136, v96, 16, 1
	v_bfe_u32 v208, v97, 16, 1
	v_add3_u32 v136, v96, v136, s77
	v_add3_u32 v208, v97, v208, s77
	v_lshrrev_b32_e32 v136, 16, v136
	v_and_or_b32 v96, v208, s35, v136
	v_bfe_u32 v136, v98, 16, 1
	v_bfe_u32 v208, v99, 16, 1
	v_add3_u32 v136, v98, v136, s77
	v_add3_u32 v208, v99, v208, s77
	v_lshrrev_b32_e32 v136, 16, v136
	v_and_or_b32 v97, v208, s35, v136
	v_bfe_u32 v136, v100, 16, 1
	v_bfe_u32 v208, v101, 16, 1
	v_add3_u32 v136, v100, v136, s77
	v_add3_u32 v208, v101, v208, s77
	v_lshrrev_b32_e32 v136, 16, v136
	v_and_or_b32 v98, v208, s35, v136
	v_bfe_u32 v136, v102, 16, 1
	v_bfe_u32 v208, v103, 16, 1
	v_add3_u32 v136, v102, v136, s77
	v_add3_u32 v208, v103, v208, s77
	v_lshrrev_b32_e32 v136, 16, v136
	v_and_or_b32 v99, v208, s35, v136
	v_fma_f32 v104, v104, s10, v214
	v_fma_f32 v105, v105, s10, v214
	v_fma_f32 v106, v106, s10, v214
	v_fma_f32 v107, v107, s10, v214
	v_fma_f32 v108, v108, s10, v214
	v_fma_f32 v109, v109, s10, v214
	v_fma_f32 v110, v110, s10, v214
	v_fma_f32 v111, v111, s10, v214
	v_exp_f32_e32 v104, v104
	v_exp_f32_e32 v105, v105
	v_exp_f32_e32 v106, v106
	v_exp_f32_e32 v107, v107
	v_exp_f32_e32 v108, v108
	v_exp_f32_e32 v109, v109
	v_exp_f32_e32 v110, v110
	v_exp_f32_e32 v111, v111
	s_nop 0
	v_add_f32_e32 v212, v212, v104
	v_add_f32_e32 v213, v213, v105
	v_add_f32_e32 v212, v212, v106
	v_add_f32_e32 v213, v213, v107
	v_add_f32_e32 v212, v212, v108
	v_add_f32_e32 v213, v213, v109
	v_add_f32_e32 v212, v212, v110
	v_add_f32_e32 v213, v213, v111
	v_bfe_u32 v136, v104, 16, 1
	v_bfe_u32 v208, v105, 16, 1
	v_add3_u32 v136, v104, v136, s77
	v_add3_u32 v208, v105, v208, s77
	v_lshrrev_b32_e32 v136, 16, v136
	v_and_or_b32 v104, v208, s35, v136
	v_bfe_u32 v136, v106, 16, 1
	v_bfe_u32 v208, v107, 16, 1
	v_add3_u32 v136, v106, v136, s77
	v_add3_u32 v208, v107, v208, s77
	v_lshrrev_b32_e32 v136, 16, v136
	v_and_or_b32 v105, v208, s35, v136
	v_bfe_u32 v136, v108, 16, 1
	v_bfe_u32 v208, v109, 16, 1
	v_add3_u32 v136, v108, v136, s77
	v_add3_u32 v208, v109, v208, s77
	v_lshrrev_b32_e32 v136, 16, v136
	v_and_or_b32 v106, v208, s35, v136
	v_bfe_u32 v136, v110, 16, 1
	v_bfe_u32 v208, v111, 16, 1
	v_add3_u32 v136, v110, v136, s77
	v_add3_u32 v208, v111, v208, s77
	v_lshrrev_b32_e32 v136, 16, v136
	v_and_or_b32 v107, v208, s35, v136
	v_fma_f32 v112, v112, s10, v214
	v_fma_f32 v113, v113, s10, v214
	v_fma_f32 v114, v114, s10, v214
	v_fma_f32 v115, v115, s10, v214
	v_fma_f32 v116, v116, s10, v214
	v_fma_f32 v117, v117, s10, v214
	v_fma_f32 v118, v118, s10, v214
	v_fma_f32 v119, v119, s10, v214
	v_exp_f32_e32 v112, v112
	v_exp_f32_e32 v113, v113
	v_exp_f32_e32 v114, v114
	v_exp_f32_e32 v115, v115
	v_exp_f32_e32 v116, v116
	v_exp_f32_e32 v117, v117
	v_exp_f32_e32 v118, v118
	v_exp_f32_e32 v119, v119
	s_nop 0
	v_add_f32_e32 v212, v212, v112
	v_add_f32_e32 v213, v213, v113
	v_add_f32_e32 v212, v212, v114
	v_add_f32_e32 v213, v213, v115
	v_add_f32_e32 v212, v212, v116
	v_add_f32_e32 v213, v213, v117
	v_add_f32_e32 v212, v212, v118
	v_add_f32_e32 v213, v213, v119
	v_bfe_u32 v136, v112, 16, 1
	v_bfe_u32 v208, v113, 16, 1
	v_add3_u32 v136, v112, v136, s77
	v_add3_u32 v208, v113, v208, s77
	v_lshrrev_b32_e32 v136, 16, v136
	v_and_or_b32 v112, v208, s35, v136
	v_bfe_u32 v136, v114, 16, 1
	v_bfe_u32 v208, v115, 16, 1
	v_add3_u32 v136, v114, v136, s77
	v_add3_u32 v208, v115, v208, s77
	v_lshrrev_b32_e32 v136, 16, v136
	v_and_or_b32 v113, v208, s35, v136
	v_bfe_u32 v136, v116, 16, 1
	v_bfe_u32 v208, v117, 16, 1
	v_add3_u32 v136, v116, v136, s77
	v_add3_u32 v208, v117, v208, s77
	v_lshrrev_b32_e32 v136, 16, v136
	v_and_or_b32 v114, v208, s35, v136
	v_bfe_u32 v136, v118, 16, 1
	v_bfe_u32 v208, v119, 16, 1
	v_add3_u32 v136, v118, v136, s77
	v_add3_u32 v208, v119, v208, s77
	v_lshrrev_b32_e32 v136, 16, v136
	v_and_or_b32 v115, v208, s35, v136
	v_fma_f32 v120, v120, s10, v214
	v_fma_f32 v121, v121, s10, v214
	v_fma_f32 v122, v122, s10, v214
	v_fma_f32 v123, v123, s10, v214
	v_fma_f32 v124, v124, s10, v214
	v_fma_f32 v125, v125, s10, v214
	v_fma_f32 v126, v126, s10, v214
	v_fma_f32 v127, v127, s10, v214
	v_exp_f32_e32 v120, v120
	v_exp_f32_e32 v121, v121
	v_exp_f32_e32 v122, v122
	v_exp_f32_e32 v123, v123
	v_exp_f32_e32 v124, v124
	v_exp_f32_e32 v125, v125
	v_exp_f32_e32 v126, v126
	v_exp_f32_e32 v127, v127
	s_nop 0
	v_add_f32_e32 v212, v212, v120
	v_add_f32_e32 v213, v213, v121
	v_add_f32_e32 v212, v212, v122
	v_add_f32_e32 v213, v213, v123
	v_add_f32_e32 v212, v212, v124
	v_add_f32_e32 v213, v213, v125
	v_add_f32_e32 v212, v212, v126
	v_add_f32_e32 v213, v213, v127
	v_bfe_u32 v136, v120, 16, 1
	v_bfe_u32 v208, v121, 16, 1
	v_add3_u32 v136, v120, v136, s77
	v_add3_u32 v208, v121, v208, s77
	v_lshrrev_b32_e32 v136, 16, v136
	v_and_or_b32 v120, v208, s35, v136
	v_bfe_u32 v136, v122, 16, 1
	v_bfe_u32 v208, v123, 16, 1
	v_add3_u32 v136, v122, v136, s77
	v_add3_u32 v208, v123, v208, s77
	v_lshrrev_b32_e32 v136, 16, v136
	v_and_or_b32 v121, v208, s35, v136
	v_bfe_u32 v136, v124, 16, 1
	v_bfe_u32 v208, v125, 16, 1
	v_add3_u32 v136, v124, v136, s77
	v_add3_u32 v208, v125, v208, s77
	v_lshrrev_b32_e32 v136, 16, v136
	v_and_or_b32 v122, v208, s35, v136
	v_bfe_u32 v136, v126, 16, 1
	v_bfe_u32 v208, v127, 16, 1
	v_add3_u32 v136, v126, v136, s77
	v_add3_u32 v208, v127, v208, s77
	v_lshrrev_b32_e32 v136, 16, v136
	v_and_or_b32 v123, v208, s35, v136
	v_add_f32_e32 v212, v212, v213
	global_load_dwordx4 v[4:7], v210, s[20:21] offset:256
	global_load_dwordx4 v[12:15], v210, s[22:23] offset:256
	global_load_dwordx4 v[20:23], v210, s[16:17] offset:384
	global_load_dwordx4 v[28:31], v210, s[18:19] offset:384
	global_load_dwordx4 v[36:39], v210, s[20:21] offset:384
	global_load_dwordx4 v[44:47], v210, s[22:23] offset:384
	global_load_dwordx4 v[52:55], v210, s[16:17] offset:512
	global_load_dwordx4 v[60:63], v210, s[18:19] offset:512
	global_load_dwordx4 v[68:71], v210, s[20:21] offset:512
	global_load_dwordx4 v[76:79], v210, s[22:23] offset:512
	global_load_dwordx4 v[84:87], v210, s[16:17] offset:640
	global_load_dwordx4 v[92:95], v210, s[18:19] offset:640
	global_load_dwordx4 v[100:103], v210, s[20:21] offset:640
	global_load_dwordx4 v[108:111], v210, s[22:23] offset:640
	global_load_dwordx4 v[116:119], v210, s[16:17] offset:768
	global_load_dwordx4 v[124:127], v210, s[18:19] offset:768
	s_waitcnt vmcnt(25)
	v_mfma_f32_16x16x32_bf16 v[128:131], v[138:141], v[0:3], 0
	global_load_dwordx4 v[138:141], v210, s[20:21] offset:768
	s_waitcnt vmcnt(25)
	v_mfma_f32_16x16x32_bf16 v[132:135], v[142:145], v[0:3], 0
	global_load_dwordx4 v[142:145], v210, s[22:23] offset:768
	s_waitcnt vmcnt(25)
	v_mfma_f32_16x16x32_bf16 v[178:181], v[146:149], v[0:3], 0
	global_load_dwordx4 v[146:149], v210, s[16:17] offset:896
	s_waitcnt vmcnt(25)
	v_mfma_f32_16x16x32_bf16 v[182:185], v[150:153], v[0:3], 0
	global_load_dwordx4 v[150:153], v210, s[18:19] offset:896
	s_waitcnt vmcnt(25)
	v_mfma_f32_16x16x32_bf16 v[128:131], v[154:157], v[8:11], v[128:131]
	global_load_dwordx4 v[154:157], v210, s[20:21] offset:896
	s_waitcnt vmcnt(25)
	v_mfma_f32_16x16x32_bf16 v[132:135], v[158:161], v[8:11], v[132:135]
	global_load_dwordx4 v[158:161], v210, s[22:23] offset:896
	s_waitcnt vmcnt(25)
	v_mfma_f32_16x16x32_bf16 v[178:181], v[162:165], v[8:11], v[178:181]
	global_load_dwordx4 v[162:165], v211, s[24:25] offset:0
	s_waitcnt vmcnt(25)
	v_mfma_f32_16x16x32_bf16 v[182:185], v[166:169], v[8:11], v[182:185]
	global_load_dwordx4 v[166:169], v211, s[26:27] offset:0
	s_waitcnt vmcnt(25)
	v_mfma_f32_16x16x32_bf16 v[128:131], v[170:173], v[16:19], v[128:131]
	global_load_dwordx4 v[170:173], v211, s[36:37] offset:0
	s_waitcnt vmcnt(25)
	v_mfma_f32_16x16x32_bf16 v[132:135], v[174:177], v[16:19], v[132:135]
	global_load_dwordx4 v[174:177], v211, s[0:1] offset:0
	s_waitcnt vmcnt(25)
	v_mfma_f32_16x16x32_bf16 v[178:181], v[4:7], v[16:19], v[178:181]
	global_load_dwordx4 v[4:7], v211, s[24:25] offset:64
	s_waitcnt vmcnt(25)
	v_mfma_f32_16x16x32_bf16 v[182:185], v[12:15], v[16:19], v[182:185]
	global_load_dwordx4 v[12:15], v211, s[26:27] offset:64
	s_waitcnt vmcnt(25)
	v_mfma_f32_16x16x32_bf16 v[128:131], v[20:23], v[24:27], v[128:131]
	global_load_dwordx4 v[20:23], v211, s[36:37] offset:64
	s_waitcnt vmcnt(25)
	v_mfma_f32_16x16x32_bf16 v[132:135], v[28:31], v[24:27], v[132:135]
	global_load_dwordx4 v[28:31], v211, s[0:1] offset:64
	s_waitcnt vmcnt(25)
	v_mfma_f32_16x16x32_bf16 v[178:181], v[36:39], v[24:27], v[178:181]
	global_load_dwordx4 v[36:39], v211, s[24:25] offset:128
	s_waitcnt vmcnt(25)
	v_mfma_f32_16x16x32_bf16 v[182:185], v[44:47], v[24:27], v[182:185]
	global_load_dwordx4 v[44:47], v211, s[26:27] offset:128
	s_waitcnt vmcnt(25)
	v_mfma_f32_16x16x32_bf16 v[128:131], v[52:55], v[32:35], v[128:131]
	global_load_dwordx4 v[52:55], v211, s[36:37] offset:128
	s_waitcnt vmcnt(25)
	v_mfma_f32_16x16x32_bf16 v[132:135], v[60:63], v[32:35], v[132:135]
	global_load_dwordx4 v[60:63], v211, s[0:1] offset:128
	s_waitcnt vmcnt(25)
	v_mfma_f32_16x16x32_bf16 v[178:181], v[68:71], v[32:35], v[178:181]
	global_load_dwordx4 v[68:71], v211, s[24:25] offset:192
	s_waitcnt vmcnt(25)
	v_mfma_f32_16x16x32_bf16 v[182:185], v[76:79], v[32:35], v[182:185]
	global_load_dwordx4 v[76:79], v211, s[26:27] offset:192
	s_waitcnt vmcnt(25)
	v_mfma_f32_16x16x32_bf16 v[128:131], v[84:87], v[40:43], v[128:131]
	global_load_dwordx4 v[84:87], v211, s[36:37] offset:192
	s_waitcnt vmcnt(25)
	v_mfma_f32_16x16x32_bf16 v[132:135], v[92:95], v[40:43], v[132:135]
	global_load_dwordx4 v[92:95], v211, s[0:1] offset:192
	s_waitcnt vmcnt(25)
	v_mfma_f32_16x16x32_bf16 v[178:181], v[100:103], v[40:43], v[178:181]
	global_load_dwordx4 v[100:103], v211, s[24:25] offset:256
	s_waitcnt vmcnt(25)
	v_mfma_f32_16x16x32_bf16 v[182:185], v[108:111], v[40:43], v[182:185]
	global_load_dwordx4 v[108:111], v211, s[26:27] offset:256
	s_waitcnt vmcnt(25)
	v_mfma_f32_16x16x32_bf16 v[128:131], v[116:119], v[48:51], v[128:131]
	global_load_dwordx4 v[116:119], v211, s[36:37] offset:256
	s_waitcnt vmcnt(25)
	v_mfma_f32_16x16x32_bf16 v[132:135], v[124:127], v[48:51], v[132:135]
	global_load_dwordx4 v[124:127], v211, s[0:1] offset:256
	s_waitcnt vmcnt(25)
	v_mfma_f32_16x16x32_bf16 v[178:181], v[138:141], v[48:51], v[178:181]
	global_load_dwordx4 v[138:141], v211, s[24:25] offset:320
	s_waitcnt vmcnt(25)
	v_mfma_f32_16x16x32_bf16 v[182:185], v[142:145], v[48:51], v[182:185]
	global_load_dwordx4 v[142:145], v211, s[26:27] offset:320
	s_waitcnt vmcnt(25)
	v_mfma_f32_16x16x32_bf16 v[128:131], v[146:149], v[56:59], v[128:131]
	global_load_dwordx4 v[146:149], v211, s[36:37] offset:320
	s_waitcnt vmcnt(25)
	v_mfma_f32_16x16x32_bf16 v[132:135], v[150:153], v[56:59], v[132:135]
	global_load_dwordx4 v[150:153], v211, s[0:1] offset:320
	s_waitcnt vmcnt(25)
	v_mfma_f32_16x16x32_bf16 v[178:181], v[154:157], v[56:59], v[178:181]
	global_load_dwordx4 v[154:157], v211, s[24:25] offset:384
	s_waitcnt vmcnt(25)
	v_mfma_f32_16x16x32_bf16 v[182:185], v[158:161], v[56:59], v[182:185]
	global_load_dwordx4 v[158:161], v211, s[26:27] offset:384
	s_waitcnt vmcnt(25)
	v_mfma_f32_16x16x32_bf16 v[128:131], v[162:165], v[64:67], v[128:131]
	global_load_dwordx4 v[162:165], v211, s[36:37] offset:384
	s_waitcnt vmcnt(25)
	v_mfma_f32_16x16x32_bf16 v[132:135], v[166:169], v[64:67], v[132:135]
	global_load_dwordx4 v[166:169], v211, s[0:1] offset:384
	s_waitcnt vmcnt(25)
	v_mfma_f32_16x16x32_bf16 v[178:181], v[170:173], v[64:67], v[178:181]
	global_load_dwordx4 v[170:173], v211, s[24:25] offset:448
	s_waitcnt vmcnt(25)
	v_mfma_f32_16x16x32_bf16 v[182:185], v[174:177], v[64:67], v[182:185]
	global_load_dwordx4 v[174:177], v211, s[26:27] offset:448
	s_waitcnt vmcnt(25)
	v_mfma_f32_16x16x32_bf16 v[128:131], v[4:7], v[72:75], v[128:131]
	global_load_dwordx4 v[4:7], v211, s[36:37] offset:448
	s_waitcnt vmcnt(25)
	v_mfma_f32_16x16x32_bf16 v[132:135], v[12:15], v[72:75], v[132:135]
	global_load_dwordx4 v[12:15], v211, s[0:1] offset:448
	s_waitcnt vmcnt(25)
	v_mfma_f32_16x16x32_bf16 v[178:181], v[20:23], v[72:75], v[178:181]
	s_waitcnt vmcnt(24)
	v_mfma_f32_16x16x32_bf16 v[182:185], v[28:31], v[72:75], v[182:185]
	s_waitcnt vmcnt(23)
	v_mfma_f32_16x16x32_bf16 v[128:131], v[36:39], v[80:83], v[128:131]
	s_waitcnt vmcnt(22)
	v_mfma_f32_16x16x32_bf16 v[132:135], v[44:47], v[80:83], v[132:135]
	s_waitcnt vmcnt(21)
	v_mfma_f32_16x16x32_bf16 v[178:181], v[52:55], v[80:83], v[178:181]
	s_waitcnt vmcnt(20)
	v_mfma_f32_16x16x32_bf16 v[182:185], v[60:63], v[80:83], v[182:185]
	s_waitcnt vmcnt(19)
	v_mfma_f32_16x16x32_bf16 v[128:131], v[68:71], v[88:91], v[128:131]
	s_waitcnt vmcnt(18)
	v_mfma_f32_16x16x32_bf16 v[132:135], v[76:79], v[88:91], v[132:135]
	s_waitcnt vmcnt(17)
	v_mfma_f32_16x16x32_bf16 v[178:181], v[84:87], v[88:91], v[178:181]
	s_waitcnt vmcnt(16)
	v_mfma_f32_16x16x32_bf16 v[182:185], v[92:95], v[88:91], v[182:185]
	s_waitcnt vmcnt(15)
	v_mfma_f32_16x16x32_bf16 v[128:131], v[100:103], v[96:99], v[128:131]
	s_waitcnt vmcnt(14)
	v_mfma_f32_16x16x32_bf16 v[132:135], v[108:111], v[96:99], v[132:135]
	s_waitcnt vmcnt(13)
	v_mfma_f32_16x16x32_bf16 v[178:181], v[116:119], v[96:99], v[178:181]
	s_waitcnt vmcnt(12)
	v_mfma_f32_16x16x32_bf16 v[182:185], v[124:127], v[96:99], v[182:185]
	s_waitcnt vmcnt(11)
	v_mfma_f32_16x16x32_bf16 v[128:131], v[138:141], v[104:107], v[128:131]
	s_waitcnt vmcnt(10)
	v_mfma_f32_16x16x32_bf16 v[132:135], v[142:145], v[104:107], v[132:135]
	s_waitcnt vmcnt(9)
	v_mfma_f32_16x16x32_bf16 v[178:181], v[146:149], v[104:107], v[178:181]
	s_waitcnt vmcnt(8)
	v_mfma_f32_16x16x32_bf16 v[182:185], v[150:153], v[104:107], v[182:185]
	s_waitcnt vmcnt(7)
	v_mfma_f32_16x16x32_bf16 v[128:131], v[154:157], v[112:115], v[128:131]
	s_waitcnt vmcnt(6)
	v_mfma_f32_16x16x32_bf16 v[132:135], v[158:161], v[112:115], v[132:135]
	s_waitcnt vmcnt(5)
	v_mfma_f32_16x16x32_bf16 v[178:181], v[162:165], v[112:115], v[178:181]
	s_waitcnt vmcnt(4)
	v_mfma_f32_16x16x32_bf16 v[182:185], v[166:169], v[112:115], v[182:185]
	s_waitcnt vmcnt(3)
	v_mfma_f32_16x16x32_bf16 v[128:131], v[170:173], v[120:123], v[128:131]
	s_waitcnt vmcnt(2)
	v_mfma_f32_16x16x32_bf16 v[132:135], v[174:177], v[120:123], v[132:135]
	s_waitcnt vmcnt(1)
	v_mfma_f32_16x16x32_bf16 v[178:181], v[4:7], v[120:123], v[178:181]
	s_waitcnt vmcnt(0)
	v_mfma_f32_16x16x32_bf16 v[182:185], v[12:15], v[120:123], v[182:185]
	ds_bpermute_b32 v136, v215, v212
	s_waitcnt lgkmcnt(0)
	v_add_f32_e32 v212, v212, v136
	ds_bpermute_b32 v136, v216, v212
	s_waitcnt lgkmcnt(0)
	v_add_f32_e32 v212, v212, v136
	v_rcp_f32_e32 v213, v212
	s_nop 0
	v_fma_f32 v136, -v212, v213, 1.0
	v_fma_f32 v213, v136, v213, v213
	v_mul_u32_u24_e32 v208, 0x600, v206
	v_lshl_add_u32 v208, v207, 3, v208
	s_add_u32 s10, s4, s38
	s_addc_u32 s11, s5, 0
	s_nop 2
	v_mul_f32_e32 v128, v128, v213
	v_mul_f32_e32 v129, v129, v213
	v_mul_f32_e32 v130, v130, v213
	v_mul_f32_e32 v131, v131, v213
	v_bfe_u32 v136, v128, 16, 1
	v_bfe_u32 v209, v129, 16, 1
	v_add3_u32 v136, v128, v136, s77
	v_add3_u32 v209, v129, v209, s77
	v_lshrrev_b32_e32 v136, 16, v136
	v_and_or_b32 v128, v209, s35, v136
	v_bfe_u32 v136, v130, 16, 1
	v_bfe_u32 v209, v131, 16, 1
	v_add3_u32 v136, v130, v136, s77
	v_add3_u32 v209, v131, v209, s77
	v_lshrrev_b32_e32 v136, 16, v136
	v_and_or_b32 v129, v209, s35, v136
	global_store_dwordx2 v208, v[128:129], s[10:11] offset:0
	v_mul_f32_e32 v132, v132, v213
	v_mul_f32_e32 v133, v133, v213
	v_mul_f32_e32 v134, v134, v213
	v_mul_f32_e32 v135, v135, v213
	v_bfe_u32 v136, v132, 16, 1
	v_bfe_u32 v209, v133, 16, 1
	v_add3_u32 v136, v132, v136, s77
	v_add3_u32 v209, v133, v209, s77
	v_lshrrev_b32_e32 v136, 16, v136
	v_and_or_b32 v132, v209, s35, v136
	v_bfe_u32 v136, v134, 16, 1
	v_bfe_u32 v209, v135, 16, 1
	v_add3_u32 v136, v134, v136, s77
	v_add3_u32 v209, v135, v209, s77
	v_lshrrev_b32_e32 v136, 16, v136
	v_and_or_b32 v133, v209, s35, v136
	global_store_dwordx2 v208, v[132:133], s[10:11] offset:32
	v_mul_f32_e32 v178, v178, v213
	v_mul_f32_e32 v179, v179, v213
	v_mul_f32_e32 v180, v180, v213
	v_mul_f32_e32 v181, v181, v213
	v_bfe_u32 v136, v178, 16, 1
	v_bfe_u32 v209, v179, 16, 1
	v_add3_u32 v136, v178, v136, s77
	v_add3_u32 v209, v179, v209, s77
	v_lshrrev_b32_e32 v136, 16, v136
	v_and_or_b32 v178, v209, s35, v136
	v_bfe_u32 v136, v180, 16, 1
	v_bfe_u32 v209, v181, 16, 1
	v_add3_u32 v136, v180, v136, s77
	v_add3_u32 v209, v181, v209, s77
	v_lshrrev_b32_e32 v136, 16, v136
	v_and_or_b32 v179, v209, s35, v136
	global_store_dwordx2 v208, v[178:179], s[10:11] offset:64
	v_mul_f32_e32 v182, v182, v213
	v_mul_f32_e32 v183, v183, v213
	v_mul_f32_e32 v184, v184, v213
	v_mul_f32_e32 v185, v185, v213
	v_bfe_u32 v136, v182, 16, 1
	v_bfe_u32 v209, v183, 16, 1
	v_add3_u32 v136, v182, v136, s77
	v_add3_u32 v209, v183, v209, s77
	v_lshrrev_b32_e32 v136, 16, v136
	v_and_or_b32 v182, v209, s35, v136
	v_bfe_u32 v136, v184, 16, 1
	v_bfe_u32 v209, v185, 16, 1
	v_add3_u32 v136, v184, v136, s77
	v_add3_u32 v209, v185, v209, s77
	v_lshrrev_b32_e32 v136, 16, v136
	v_and_or_b32 v183, v209, s35, v136
	global_store_dwordx2 v208, v[182:183], s[10:11] offset:96
